# version 97 plus residual epilogue: the leading half issues its sixteen residual loads before its re-alignment barrier
# baseline (speedup 1.0000x reference)
; #define PG8_BAR __builtin_amdgcn_s_barrier()
; template <class Epi, class Sched, bool ALIGN_EPI = false, bool SP2 = false>
; __device__ __forceinline__ void gemm_phase(PG8_LAS unsigned char* lds, const Gemm g, const Sched& S, const Epi& E, const int tid_in) {
;     ...
;             PG8_WAIT_V(8); PG8_WAIT_L(0); PG8_BAR; PG8_MMA(0, 0, At, B0); PG8_MMA(0, 1, At, B1); PG8_BAR; PG8_SCHED;
;             PG8_LDA(At, 1, 1); PG8_STAGE(PG8_SB(1, 0), b3, voffB); PG8_STAGE(PG8_SB(1, 1), b3 + hstep, voffB); PG8_STAGE(PG8_SA(1, 0), a3, voffA);
;             PG8_WAIT_V(8); PG8_WAIT_L(0); PG8_BAR; PG8_MMA(1, 0, At, B0); PG8_MMA(1, 1, At, B1); PG8_BAR; PG8_SCHED;
;             } else {
;             PG8_LDB(B0, 0, 0); PG8_SCHED; PG8_LDA(At, 0, 0); PG8_STAGE(PG8_SA(1, 1), a1 + hstep, voffA);
;             PG8_WAIT_L(8); PG8_BAR; PG8_WAIT_L(0); PG8_MMA(0, 0, At, B0); PG8_BAR; PG8_SCHED;
;             PG8_LDB(B1, 0, 1); PG8_STAGE(PG8_SB(0, 0), b2, voffB);
;             PG8_BAR; PG8_WAIT_L(0); PG8_MMA(0, 1, At, B1); PG8_BAR;
;             PG8_LDA(At, 0, 1); PG8_STAGE(PG8_SA(0, 0), a2, voffA);
;             PG8_BAR; PG8_WAIT_L(0); PG8_MMA(1, 0, At, B0); PG8_BAR; PG8_SCHED;
;             PG8_STAGE(PG8_SB(0, 1), b2 + hstep, voffB);
;             PG8_WAIT_V(6); PG8_BAR; PG8_MMA(1, 1, At, B1); PG8_BAR;
;             PG8_LDB(B0, 1, 0); PG8_SCHED; PG8_LDA(At, 1, 0); PG8_STAGE(PG8_SA(0, 1), a2 + hstep, voffA);
;             PG8_WAIT_L(8); PG8_BAR; PG8_WAIT_L(0); PG8_MMA(0, 0, At, B0); PG8_BAR; PG8_SCHED;
;             PG8_LDB(B1, 1, 1); PG8_STAGE(PG8_SB(1, 0), b3, voffB);
;             PG8_BAR; PG8_WAIT_L(0); PG8_MMA(0, 1, At, B1); PG8_BAR;
;             PG8_LDA(At, 1, 1); PG8_STAGE(PG8_SA(1, 0), a3, voffA);
;             PG8_BAR; PG8_WAIT_L(0); PG8_MMA(1, 0, At, B0); PG8_BAR; PG8_SCHED;
;             PG8_STAGE(PG8_SB(1, 1), b3 + hstep, voffB);
;             PG8_WAIT_V(6); PG8_BAR; PG8_MMA(1, 1, At, B1); PG8_BAR;
;             }
;         }
;         if constexpr (ALIGN_EPI) { if (wr == 0) PG8_BAR; }
;     __device__ __forceinline__ void operator()(const f32x4 (&acc)[2][2][4][2], const Unit& u, int wr, int wc, int fr, int fq) const {
;         const int row0 = u.pm * BM + wr * 64 + fr, col0 = u.pn * BM + wc * 32 + 8 * fq;
;         u32x4 xv[2][4][2];
; #pragma unroll
;         for (int ai = 0; ai < 2; ++ai)
; #pragma unroll
;             for (int m = 0; m < 4; ++m)
; #pragma unroll
.Lrt_join_3:
	s_waitcnt lgkmcnt(0)
	s_barrier
	v_mfma_f32_16x16x32_bf16 v[66:69], v[126:129], v[158:161], v[66:69]
	v_mfma_f32_16x16x32_bf16 v[66:69], v[130:133], v[162:165], v[66:69]
	v_mfma_f32_16x16x32_bf16 v[50:53], v[126:129], v[170:173], v[50:53]
	v_mfma_f32_16x16x32_bf16 v[50:53], v[130:133], v[178:181], v[50:53]
	v_mfma_f32_16x16x32_bf16 v[34:37], v[126:129], v[182:185], v[34:37]
	v_mfma_f32_16x16x32_bf16 v[34:37], v[130:133], v[186:189], v[34:37]
	v_mfma_f32_16x16x32_bf16 v[18:21], v[126:129], v[190:193], v[18:21]
	v_mfma_f32_16x16x32_bf16 v[18:21], v[130:133], v[210:213], v[18:21]
	v_mfma_f32_16x16x32_bf16 v[62:65], v[134:137], v[158:161], v[62:65]
	v_mfma_f32_16x16x32_bf16 v[62:65], v[138:141], v[162:165], v[62:65]
	v_mfma_f32_16x16x32_bf16 v[46:49], v[134:137], v[170:173], v[46:49]
	v_mfma_f32_16x16x32_bf16 v[46:49], v[138:141], v[178:181], v[46:49]
	v_mfma_f32_16x16x32_bf16 v[30:33], v[134:137], v[182:185], v[30:33]
	v_mfma_f32_16x16x32_bf16 v[30:33], v[138:141], v[186:189], v[30:33]
	v_mfma_f32_16x16x32_bf16 v[14:17], v[134:137], v[190:193], v[14:17]
	v_mfma_f32_16x16x32_bf16 v[14:17], v[138:141], v[210:213], v[14:17]
	v_mfma_f32_16x16x32_bf16 v[58:61], v[142:145], v[158:161], v[58:61]
	v_mfma_f32_16x16x32_bf16 v[58:61], v[146:149], v[162:165], v[58:61]
	v_mfma_f32_16x16x32_bf16 v[42:45], v[142:145], v[170:173], v[42:45]
	v_mfma_f32_16x16x32_bf16 v[42:45], v[146:149], v[178:181], v[42:45]
	v_mfma_f32_16x16x32_bf16 v[26:29], v[142:145], v[182:185], v[26:29]
	v_mfma_f32_16x16x32_bf16 v[26:29], v[146:149], v[186:189], v[26:29]
	v_mfma_f32_16x16x32_bf16 v[10:13], v[142:145], v[190:193], v[10:13]
	v_mfma_f32_16x16x32_bf16 v[10:13], v[146:149], v[210:213], v[10:13]
	v_mfma_f32_16x16x32_bf16 v[54:57], v[150:153], v[158:161], v[54:57]
	v_mfma_f32_16x16x32_bf16 v[54:57], v[154:157], v[162:165], v[54:57]
	v_mfma_f32_16x16x32_bf16 v[38:41], v[150:153], v[170:173], v[38:41]
	v_mfma_f32_16x16x32_bf16 v[38:41], v[154:157], v[178:181], v[38:41]
	v_mfma_f32_16x16x32_bf16 v[22:25], v[150:153], v[182:185], v[22:25]
	v_mfma_f32_16x16x32_bf16 v[22:25], v[154:157], v[186:189], v[22:25]
	v_mfma_f32_16x16x32_bf16 v[6:9], v[150:153], v[190:193], v[6:9]
	v_mfma_f32_16x16x32_bf16 v[6:9], v[154:157], v[210:213], v[6:9]
	s_barrier
	s_add_u32 s10, s10, 0x100
	s_addc_u32 s11, s11, 0
	s_add_u32 s14, s14, 0x100
	s_addc_u32 s15, s15, 0
	s_cmp_ge_u32 s51, s30
	s_mov_b32 s12, s51
	s_cbranch_scc0 .LBB0_177
	v_lshl_or_b32 v126, s49, 8, v248
	v_lshl_add_u32 v210, s50, 8, v246
	v_ashrrev_i32_e32 v127, 31, v126
	v_lshlrev_b64 v[212:213], 1, v[126:127]
	v_ashrrev_i32_e32 v211, 31, v210
	v_lshl_add_u64 v[126:127], s[84:85], 0, v[212:213]
	v_lshlrev_b64 v[228:229], 11, v[210:211]
	v_lshl_add_u64 v[128:129], v[126:127], 0, v[228:229]
	global_load_dwordx4 v[238:241], v[128:129], off
	global_load_dwordx4 v[190:193], v[128:129], off offset:256
	v_or_b32_e32 v128, 16, v210
	v_ashrrev_i32_e32 v129, 31, v128
	v_lshlrev_b64 v[226:227], 11, v[128:129]
	v_lshl_add_u64 v[128:129], v[126:127], 0, v[226:227]
	global_load_dwordx4 v[186:189], v[128:129], off
	global_load_dwordx4 v[182:185], v[128:129], off offset:256
	v_or_b32_e32 v128, 32, v210
	v_ashrrev_i32_e32 v129, 31, v128
	v_lshlrev_b64 v[224:225], 11, v[128:129]
	v_lshl_add_u64 v[128:129], v[126:127], 0, v[224:225]
	global_load_dwordx4 v[178:181], v[128:129], off
	global_load_dwordx4 v[170:173], v[128:129], off offset:256
	v_or_b32_e32 v128, 48, v210
	v_ashrrev_i32_e32 v129, 31, v128
	s_mov_b64 s[10:11], 0x40000
	v_lshlrev_b64 v[222:223], 11, v[128:129]
	v_lshl_add_u64 v[220:221], v[228:229], 0, s[10:11]
	s_mov_b64 s[10:11], 0x48000
	v_lshl_add_u64 v[128:129], v[126:127], 0, v[222:223]
	v_lshl_add_u64 v[218:219], v[228:229], 0, s[10:11]
	s_mov_b64 s[10:11], 0x50000
	global_load_dwordx4 v[162:165], v[128:129], off
	global_load_dwordx4 v[154:157], v[128:129], off offset:256
	v_lshl_add_u64 v[128:129], v[126:127], 0, v[220:221]
	v_lshl_add_u64 v[216:217], v[228:229], 0, s[10:11]
	s_mov_b64 s[10:11], 0x58000
	global_load_dwordx4 v[158:161], v[128:129], off
	global_load_dwordx4 v[150:153], v[128:129], off offset:256
	v_lshl_add_u64 v[128:129], v[126:127], 0, v[218:219]
	v_lshl_add_u64 v[214:215], v[228:229], 0, s[10:11]
	global_load_dwordx4 v[146:149], v[128:129], off
	global_load_dwordx4 v[142:145], v[128:129], off offset:256
	v_lshl_add_u64 v[128:129], v[126:127], 0, v[216:217]
	v_lshl_add_u64 v[126:127], v[126:127], 0, v[214:215]
	global_load_dwordx4 v[138:141], v[128:129], off
	global_load_dwordx4 v[134:137], v[128:129], off offset:256
	global_load_dwordx4 v[130:133], v[126:127], off
	s_nop 0
	global_load_dwordx4 v[126:129], v[126:127], off offset:256
	s_and_b64 vcc, exec, s[42:43]
	s_cbranch_vccz .LBB0_180
	s_barrier
; __device__ __forceinline__ unsigned cvt_pk_bf16(float lo, float hi) { unsigned r; asm volatile("v_cvt_pk_bf16_f32 %0, %1, %2" : "=v"(r) : "v"(lo), "v"(hi)); return r; }
;     __device__ __forceinline__ void operator()(const f32x4 (&acc)[2][2][4][2], const Unit& u, int wr, int wc, int fr, int fq) const {
;     ...
;             for (int m = 0; m < 4; ++m) {
;                 const int row = row0 + ai * HALF + m * 16;
;                 float ss = 0.f;
; #pragma unroll
;                 for (int bj = 0; bj < 2; ++bj) {
;                     const u32x4 xo = xv[ai][m][bj]; u32x4 w;
; #pragma unroll
;                     for (int k = 0; k < 4; ++k) {
;                         const float a0 = __uint_as_float(xo[k] << 16) + acc[ai][bj][m][k >> 1][(k & 1) * 2] * scale, a1 = __uint_as_float(xo[k] & 0xffff0000u) + acc[ai][bj][m][k >> 1][(k & 1) * 2 + 1] * scale;
;                         const unsigned p = cvt_pk_bf16(a0, a1); w[k] = p;
;                         const float r0 = __uint_as_float(p << 16), r1 = __uint_as_float(p & 0xffff0000u); ss += r0 * r0 + r1 * r1;
;                     }
;                     *(u32x4*)(xb + (size_t)row * 1024 + col0 + bj * HALF) = w;
;                 }
;                 ssv[ai][m] = ss;
;             }
.LBB0_180:
	s_waitcnt vmcnt(15)
	v_lshlrev_b32_e32 v250, 16, v238
	v_fmac_f32_e32 v250, v2, v174
	v_and_b32_e32 v174, 0xffff0000, v238
	v_fmac_f32_e32 v174, v2, v175
	v_cvt_pk_bf16_f32 v174, v250, v174
	s_nop 0
	v_and_b32_e32 v238, 0xffff0000, v174
	v_lshlrev_b32_e32 v175, 16, v174
	v_mul_f32_e32 v238, v238, v238
	v_fmac_f32_e32 v238, v175, v175
	v_lshlrev_b32_e32 v175, 16, v239
	v_fmac_f32_e32 v175, v2, v176
	v_and_b32_e32 v176, 0xffff0000, v239
	v_fmac_f32_e32 v176, v2, v177
	v_cvt_pk_bf16_f32 v175, v175, v176
	s_nop 0
	v_and_b32_e32 v177, 0xffff0000, v175
	v_lshlrev_b32_e32 v176, 16, v175
	v_mul_f32_e32 v177, v177, v177
	v_fmac_f32_e32 v177, v176, v176
	v_lshlrev_b32_e32 v176, 16, v240
	v_fmac_f32_e32 v176, v2, v166
	v_and_b32_e32 v166, 0xffff0000, v240
	v_fmac_f32_e32 v166, v2, v167
	v_cvt_pk_bf16_f32 v176, v176, v166
	v_add_f32_e32 v177, v238, v177
	v_and_b32_e32 v167, 0xffff0000, v176
	v_lshlrev_b32_e32 v166, 16, v176
	v_mul_f32_e32 v167, v167, v167
	v_fmac_f32_e32 v167, v166, v166
	v_add_f32_e32 v166, v177, v167
	v_lshlrev_b32_e32 v167, 16, v241
	v_fmac_f32_e32 v167, v2, v168
	v_and_b32_e32 v168, 0xffff0000, v241
	v_fmac_f32_e32 v168, v2, v169
	v_cvt_pk_bf16_f32 v177, v167, v168
	s_waitcnt vmcnt(14)
	v_lshlrev_b32_e32 v169, 16, v190
	v_and_b32_e32 v168, 0xffff0000, v177
	v_lshlrev_b32_e32 v167, 16, v177
	v_mul_f32_e32 v168, v168, v168
	v_fmac_f32_e32 v168, v167, v167
	v_add_f32_e32 v168, v166, v168
	v_lshl_add_u64 v[166:167], s[84:85], 0, v[228:229]
	v_fmac_f32_e32 v169, v2, v122
	v_and_b32_e32 v122, 0xffff0000, v190
	v_lshl_add_u64 v[166:167], v[166:167], 0, v[212:213]
	v_fmac_f32_e32 v122, v2, v123
	global_store_dwordx4 v[166:167], v[174:177], off
	v_cvt_pk_bf16_f32 v122, v169, v122
	s_nop 0
	v_and_b32_e32 v169, 0xffff0000, v122
	v_lshlrev_b32_e32 v123, 16, v122
	v_mul_f32_e32 v169, v169, v169
	v_fmac_f32_e32 v169, v123, v123
	v_lshlrev_b32_e32 v123, 16, v191
	v_fmac_f32_e32 v123, v2, v124
	v_and_b32_e32 v124, 0xffff0000, v191
	v_fmac_f32_e32 v124, v2, v125
	v_cvt_pk_bf16_f32 v123, v123, v124
	v_add_f32_e32 v168, v168, v169
	v_and_b32_e32 v125, 0xffff0000, v123
	v_lshlrev_b32_e32 v124, 16, v123
	v_mul_f32_e32 v125, v125, v125
	v_fmac_f32_e32 v125, v124, v124
	v_lshlrev_b32_e32 v124, 16, v192
	v_fmac_f32_e32 v124, v2, v118
	v_and_b32_e32 v118, 0xffff0000, v192
	v_fmac_f32_e32 v118, v2, v119
	v_cvt_pk_bf16_f32 v124, v124, v118
	v_add_f32_e32 v125, v168, v125
	v_and_b32_e32 v119, 0xffff0000, v124
	v_lshlrev_b32_e32 v118, 16, v124
	v_mul_f32_e32 v119, v119, v119
	v_fmac_f32_e32 v119, v118, v118
	v_add_f32_e32 v118, v125, v119
	v_lshlrev_b32_e32 v119, 16, v193
	v_fmac_f32_e32 v119, v2, v120
	v_and_b32_e32 v120, 0xffff0000, v193
	v_fmac_f32_e32 v120, v2, v121
	v_cvt_pk_bf16_f32 v125, v119, v120
	global_store_dwordx4 v[166:167], v[122:125], off offset:256
	v_and_b32_e32 v120, 0xffff0000, v125
	v_lshlrev_b32_e32 v119, 16, v125
	v_mul_f32_e32 v120, v120, v120
	v_fmac_f32_e32 v120, v119, v119
	s_waitcnt vmcnt(15)
	v_lshlrev_b32_e32 v119, 16, v186
	v_fmac_f32_e32 v119, v2, v114
	v_and_b32_e32 v114, 0xffff0000, v186
	v_fmac_f32_e32 v114, v2, v115
	v_cvt_pk_bf16_f32 v114, v119, v114
	v_add_f32_e32 v118, v118, v120
	v_and_b32_e32 v119, 0xffff0000, v114
	v_lshlrev_b32_e32 v115, 16, v114
	v_mul_f32_e32 v119, v119, v119
	v_fmac_f32_e32 v119, v115, v115
	v_lshlrev_b32_e32 v115, 16, v187
	v_fmac_f32_e32 v115, v2, v116
	v_and_b32_e32 v116, 0xffff0000, v187
	v_fmac_f32_e32 v116, v2, v117
	v_cvt_pk_bf16_f32 v115, v115, v116
	s_nop 0
	v_and_b32_e32 v117, 0xffff0000, v115
	v_lshlrev_b32_e32 v116, 16, v115
	v_mul_f32_e32 v117, v117, v117
	v_fmac_f32_e32 v117, v116, v116
	v_lshlrev_b32_e32 v116, 16, v188
	v_fmac_f32_e32 v116, v2, v110
	v_and_b32_e32 v110, 0xffff0000, v188
	v_fmac_f32_e32 v110, v2, v111
	v_cvt_pk_bf16_f32 v116, v116, v110
	v_add_f32_e32 v117, v119, v117
	v_and_b32_e32 v111, 0xffff0000, v116
	v_lshlrev_b32_e32 v110, 16, v116
	v_mul_f32_e32 v111, v111, v111
	v_fmac_f32_e32 v111, v110, v110
	v_add_f32_e32 v110, v117, v111
	v_lshlrev_b32_e32 v111, 16, v189
	v_fmac_f32_e32 v111, v2, v112
	v_and_b32_e32 v112, 0xffff0000, v189
	v_fmac_f32_e32 v112, v2, v113
	v_cvt_pk_bf16_f32 v117, v111, v112
	s_waitcnt vmcnt(14)
	v_lshlrev_b32_e32 v113, 16, v182
	v_and_b32_e32 v112, 0xffff0000, v117
	v_lshlrev_b32_e32 v111, 16, v117
	v_mul_f32_e32 v112, v112, v112
	v_fmac_f32_e32 v112, v111, v111
	v_add_f32_e32 v112, v110, v112
	v_lshl_add_u64 v[110:111], s[84:85], 0, v[226:227]
	v_fmac_f32_e32 v113, v2, v106
	v_and_b32_e32 v106, 0xffff0000, v182
	v_lshl_add_u64 v[110:111], v[110:111], 0, v[212:213]
	v_fmac_f32_e32 v106, v2, v107
	global_store_dwordx4 v[110:111], v[114:117], off
	v_cvt_pk_bf16_f32 v106, v113, v106
	s_nop 0
	v_and_b32_e32 v113, 0xffff0000, v106
	v_lshlrev_b32_e32 v107, 16, v106
	v_mul_f32_e32 v113, v113, v113
	v_fmac_f32_e32 v113, v107, v107
	v_lshlrev_b32_e32 v107, 16, v183
	v_fmac_f32_e32 v107, v2, v108
	v_and_b32_e32 v108, 0xffff0000, v183
	v_fmac_f32_e32 v108, v2, v109
	v_cvt_pk_bf16_f32 v107, v107, v108
	v_add_f32_e32 v112, v112, v113
	v_and_b32_e32 v109, 0xffff0000, v107
	v_lshlrev_b32_e32 v108, 16, v107
	v_mul_f32_e32 v109, v109, v109
	v_fmac_f32_e32 v109, v108, v108
	v_lshlrev_b32_e32 v108, 16, v184
	v_fmac_f32_e32 v108, v2, v102
	v_and_b32_e32 v102, 0xffff0000, v184
	v_fmac_f32_e32 v102, v2, v103
	v_cvt_pk_bf16_f32 v108, v108, v102
	v_add_f32_e32 v109, v112, v109
	v_and_b32_e32 v103, 0xffff0000, v108
	v_lshlrev_b32_e32 v102, 16, v108
	v_mul_f32_e32 v103, v103, v103
	v_fmac_f32_e32 v103, v102, v102
	v_add_f32_e32 v102, v109, v103
	v_lshlrev_b32_e32 v103, 16, v185
	v_fmac_f32_e32 v103, v2, v104
	v_and_b32_e32 v104, 0xffff0000, v185
	v_fmac_f32_e32 v104, v2, v105
	v_cvt_pk_bf16_f32 v109, v103, v104
	global_store_dwordx4 v[110:111], v[106:109], off offset:256
	v_and_b32_e32 v104, 0xffff0000, v109
	v_lshlrev_b32_e32 v103, 16, v109
	v_mul_f32_e32 v104, v104, v104
	v_fmac_f32_e32 v104, v103, v103
	s_waitcnt vmcnt(15)
; __device__ __forceinline__ unsigned cvt_pk_bf16(float lo, float hi) { unsigned r; asm volatile("v_cvt_pk_bf16_f32 %0, %1, %2" : "=v"(r) : "v"(lo), "v"(hi)); return r; }
;     __device__ __forceinline__ void operator()(const f32x4 (&acc)[2][2][4][2], const Unit& u, int wr, int wc, int fr, int fq) const {
;     ...
;             for (int m = 0; m < 4; ++m) {
;                 const int row = row0 + ai * HALF + m * 16;
;                 float ss = 0.f;
; #pragma unroll
;                 for (int bj = 0; bj < 2; ++bj) {
;                     const u32x4 xo = xv[ai][m][bj]; u32x4 w;
; #pragma unroll
;                     for (int k = 0; k < 4; ++k) {
;                         const float a0 = __uint_as_float(xo[k] << 16) + acc[ai][bj][m][k >> 1][(k & 1) * 2] * scale, a1 = __uint_as_float(xo[k] & 0xffff0000u) + acc[ai][bj][m][k >> 1][(k & 1) * 2 + 1] * scale;
;                         const unsigned p = cvt_pk_bf16(a0, a1); w[k] = p;
;                         const float r0 = __uint_as_float(p << 16), r1 = __uint_as_float(p & 0xffff0000u); ss += r0 * r0 + r1 * r1;
;                     }
;                     *(u32x4*)(xb + (size_t)row * 1024 + col0 + bj * HALF) = w;
;                 }
;                 ssv[ai][m] = ss;
;             }
	v_lshlrev_b32_e32 v103, 16, v178
	v_fmac_f32_e32 v103, v2, v98
	v_and_b32_e32 v98, 0xffff0000, v178
	v_fmac_f32_e32 v98, v2, v99
	v_cvt_pk_bf16_f32 v98, v103, v98
	v_add_f32_e32 v102, v102, v104
	v_and_b32_e32 v103, 0xffff0000, v98
	v_lshlrev_b32_e32 v99, 16, v98
	v_mul_f32_e32 v103, v103, v103
	v_fmac_f32_e32 v103, v99, v99
	v_lshlrev_b32_e32 v99, 16, v179
	v_fmac_f32_e32 v99, v2, v100
	v_and_b32_e32 v100, 0xffff0000, v179
	v_fmac_f32_e32 v100, v2, v101
	v_cvt_pk_bf16_f32 v99, v99, v100
	s_nop 0
	v_and_b32_e32 v101, 0xffff0000, v99
	v_lshlrev_b32_e32 v100, 16, v99
	v_mul_f32_e32 v101, v101, v101
	v_fmac_f32_e32 v101, v100, v100
	v_lshlrev_b32_e32 v100, 16, v180
	v_fmac_f32_e32 v100, v2, v94
	v_and_b32_e32 v94, 0xffff0000, v180
	v_fmac_f32_e32 v94, v2, v95
	v_cvt_pk_bf16_f32 v100, v100, v94
	v_add_f32_e32 v101, v103, v101
	v_and_b32_e32 v95, 0xffff0000, v100
	v_lshlrev_b32_e32 v94, 16, v100
	v_mul_f32_e32 v95, v95, v95
	v_fmac_f32_e32 v95, v94, v94
	v_add_f32_e32 v94, v101, v95
	v_lshlrev_b32_e32 v95, 16, v181
	v_fmac_f32_e32 v95, v2, v96
	v_and_b32_e32 v96, 0xffff0000, v181
	v_fmac_f32_e32 v96, v2, v97
	v_cvt_pk_bf16_f32 v101, v95, v96
	s_waitcnt vmcnt(14)
	v_lshlrev_b32_e32 v97, 16, v170
	v_and_b32_e32 v96, 0xffff0000, v101
	v_lshlrev_b32_e32 v95, 16, v101
	v_mul_f32_e32 v96, v96, v96
	v_fmac_f32_e32 v96, v95, v95
	v_add_f32_e32 v96, v94, v96
	v_lshl_add_u64 v[94:95], s[84:85], 0, v[224:225]
	v_fmac_f32_e32 v97, v2, v90
	v_and_b32_e32 v90, 0xffff0000, v170
	v_lshl_add_u64 v[94:95], v[94:95], 0, v[212:213]
	v_fmac_f32_e32 v90, v2, v91
	global_store_dwordx4 v[94:95], v[98:101], off
	v_cvt_pk_bf16_f32 v90, v97, v90
	s_nop 0
	v_and_b32_e32 v97, 0xffff0000, v90
	v_lshlrev_b32_e32 v91, 16, v90
	v_mul_f32_e32 v97, v97, v97
	v_fmac_f32_e32 v97, v91, v91
	v_lshlrev_b32_e32 v91, 16, v171
	v_fmac_f32_e32 v91, v2, v92
	v_and_b32_e32 v92, 0xffff0000, v171
	v_fmac_f32_e32 v92, v2, v93
	v_cvt_pk_bf16_f32 v91, v91, v92
	v_add_f32_e32 v96, v96, v97
	v_and_b32_e32 v93, 0xffff0000, v91
	v_lshlrev_b32_e32 v92, 16, v91
	v_mul_f32_e32 v93, v93, v93
	v_fmac_f32_e32 v93, v92, v92
	v_lshlrev_b32_e32 v92, 16, v172
	v_fmac_f32_e32 v92, v2, v86
	v_and_b32_e32 v86, 0xffff0000, v172
	v_fmac_f32_e32 v86, v2, v87
	v_cvt_pk_bf16_f32 v92, v92, v86
	v_add_f32_e32 v93, v96, v93
	v_and_b32_e32 v87, 0xffff0000, v92
	v_lshlrev_b32_e32 v86, 16, v92
	v_mul_f32_e32 v87, v87, v87
	v_fmac_f32_e32 v87, v86, v86
	v_add_f32_e32 v86, v93, v87
	v_lshlrev_b32_e32 v87, 16, v173
	v_fmac_f32_e32 v87, v2, v88
	v_and_b32_e32 v88, 0xffff0000, v173
	v_fmac_f32_e32 v88, v2, v89
	v_cvt_pk_bf16_f32 v93, v87, v88
	global_store_dwordx4 v[94:95], v[90:93], off offset:256
	v_and_b32_e32 v88, 0xffff0000, v93
	v_lshlrev_b32_e32 v87, 16, v93
	v_mul_f32_e32 v88, v88, v88
	v_fmac_f32_e32 v88, v87, v87
	s_waitcnt vmcnt(15)
	v_lshlrev_b32_e32 v87, 16, v162
	v_fmac_f32_e32 v87, v2, v82
	v_and_b32_e32 v82, 0xffff0000, v162
	v_fmac_f32_e32 v82, v2, v83
	v_cvt_pk_bf16_f32 v82, v87, v82
	v_add_f32_e32 v86, v86, v88
	v_and_b32_e32 v87, 0xffff0000, v82
	v_lshlrev_b32_e32 v83, 16, v82
	v_mul_f32_e32 v87, v87, v87
	v_fmac_f32_e32 v87, v83, v83
	v_lshlrev_b32_e32 v83, 16, v163
	v_fmac_f32_e32 v83, v2, v84
	v_and_b32_e32 v84, 0xffff0000, v163
	v_fmac_f32_e32 v84, v2, v85
	v_cvt_pk_bf16_f32 v83, v83, v84
	s_nop 0
	v_and_b32_e32 v85, 0xffff0000, v83
	v_lshlrev_b32_e32 v84, 16, v83
	v_mul_f32_e32 v85, v85, v85
	v_fmac_f32_e32 v85, v84, v84
	v_lshlrev_b32_e32 v84, 16, v164
	v_fmac_f32_e32 v84, v2, v78
	v_and_b32_e32 v78, 0xffff0000, v164
	v_fmac_f32_e32 v78, v2, v79
	v_cvt_pk_bf16_f32 v84, v84, v78
	v_add_f32_e32 v85, v87, v85
	v_and_b32_e32 v79, 0xffff0000, v84
	v_lshlrev_b32_e32 v78, 16, v84
	v_mul_f32_e32 v79, v79, v79
	v_fmac_f32_e32 v79, v78, v78
	v_add_f32_e32 v78, v85, v79
	v_lshlrev_b32_e32 v79, 16, v165
	v_fmac_f32_e32 v79, v2, v80
	v_and_b32_e32 v80, 0xffff0000, v165
	v_fmac_f32_e32 v80, v2, v81
	v_cvt_pk_bf16_f32 v85, v79, v80
	s_waitcnt vmcnt(14)
	v_lshlrev_b32_e32 v81, 16, v154
	v_and_b32_e32 v80, 0xffff0000, v85
	v_lshlrev_b32_e32 v79, 16, v85
	v_mul_f32_e32 v80, v80, v80
	v_fmac_f32_e32 v80, v79, v79
	v_add_f32_e32 v80, v78, v80
	v_lshl_add_u64 v[78:79], s[84:85], 0, v[222:223]
	v_fmac_f32_e32 v81, v2, v74
	v_and_b32_e32 v74, 0xffff0000, v154
	v_lshl_add_u64 v[78:79], v[78:79], 0, v[212:213]
	v_fmac_f32_e32 v74, v2, v75
	global_store_dwordx4 v[78:79], v[82:85], off
	v_cvt_pk_bf16_f32 v74, v81, v74
	s_nop 0
	v_and_b32_e32 v81, 0xffff0000, v74
	v_lshlrev_b32_e32 v75, 16, v74
	v_mul_f32_e32 v81, v81, v81
	v_fmac_f32_e32 v81, v75, v75
	v_lshlrev_b32_e32 v75, 16, v155
	v_fmac_f32_e32 v75, v2, v76
	v_and_b32_e32 v76, 0xffff0000, v155
	v_fmac_f32_e32 v76, v2, v77
	v_cvt_pk_bf16_f32 v75, v75, v76
	v_add_f32_e32 v80, v80, v81
	v_and_b32_e32 v77, 0xffff0000, v75
	v_lshlrev_b32_e32 v76, 16, v75
	v_mul_f32_e32 v77, v77, v77
	v_fmac_f32_e32 v77, v76, v76
	v_lshlrev_b32_e32 v76, 16, v156
	v_fmac_f32_e32 v76, v2, v70
	v_and_b32_e32 v70, 0xffff0000, v156
	v_fmac_f32_e32 v70, v2, v71
	v_cvt_pk_bf16_f32 v76, v76, v70
	v_add_f32_e32 v77, v80, v77
	v_and_b32_e32 v71, 0xffff0000, v76
	v_lshlrev_b32_e32 v70, 16, v76
	v_mul_f32_e32 v71, v71, v71
	v_fmac_f32_e32 v71, v70, v70
	v_add_f32_e32 v70, v77, v71
	v_lshlrev_b32_e32 v71, 16, v157
	v_fmac_f32_e32 v71, v2, v72
	v_and_b32_e32 v72, 0xffff0000, v157
	v_fmac_f32_e32 v72, v2, v73
	v_cvt_pk_bf16_f32 v77, v71, v72
	global_store_dwordx4 v[78:79], v[74:77], off offset:256
	v_and_b32_e32 v72, 0xffff0000, v77
	v_lshlrev_b32_e32 v71, 16, v77
	v_mul_f32_e32 v72, v72, v72
	v_fmac_f32_e32 v72, v71, v71
	s_waitcnt vmcnt(15)
; __device__ __forceinline__ unsigned cvt_pk_bf16(float lo, float hi) { unsigned r; asm volatile("v_cvt_pk_bf16_f32 %0, %1, %2" : "=v"(r) : "v"(lo), "v"(hi)); return r; }
;     __device__ __forceinline__ void operator()(const f32x4 (&acc)[2][2][4][2], const Unit& u, int wr, int wc, int fr, int fq) const {
;     ...
;             for (int m = 0; m < 4; ++m) {
;                 const int row = row0 + ai * HALF + m * 16;
;                 float ss = 0.f;
; #pragma unroll
;                 for (int bj = 0; bj < 2; ++bj) {
;                     const u32x4 xo = xv[ai][m][bj]; u32x4 w;
; #pragma unroll
;                     for (int k = 0; k < 4; ++k) {
;                         const float a0 = __uint_as_float(xo[k] << 16) + acc[ai][bj][m][k >> 1][(k & 1) * 2] * scale, a1 = __uint_as_float(xo[k] & 0xffff0000u) + acc[ai][bj][m][k >> 1][(k & 1) * 2 + 1] * scale;
;                         const unsigned p = cvt_pk_bf16(a0, a1); w[k] = p;
;                         const float r0 = __uint_as_float(p << 16), r1 = __uint_as_float(p & 0xffff0000u); ss += r0 * r0 + r1 * r1;
;                     }
;                     *(u32x4*)(xb + (size_t)row * 1024 + col0 + bj * HALF) = w;
;                 }
;                 ssv[ai][m] = ss;
;             }
	v_lshlrev_b32_e32 v71, 16, v158
	v_fmac_f32_e32 v71, v2, v66
	v_and_b32_e32 v66, 0xffff0000, v158
	v_fmac_f32_e32 v66, v2, v67
	v_cvt_pk_bf16_f32 v66, v71, v66
	v_add_f32_e32 v70, v70, v72
	v_and_b32_e32 v71, 0xffff0000, v66
	v_lshlrev_b32_e32 v67, 16, v66
	v_mul_f32_e32 v71, v71, v71
	v_fmac_f32_e32 v71, v67, v67
	v_lshlrev_b32_e32 v67, 16, v159
	v_fmac_f32_e32 v67, v2, v68
	v_and_b32_e32 v68, 0xffff0000, v159
	v_fmac_f32_e32 v68, v2, v69
	v_cvt_pk_bf16_f32 v67, v67, v68
	s_nop 0
	v_and_b32_e32 v69, 0xffff0000, v67
	v_lshlrev_b32_e32 v68, 16, v67
	v_mul_f32_e32 v69, v69, v69
	v_fmac_f32_e32 v69, v68, v68
	v_lshlrev_b32_e32 v68, 16, v160
	v_fmac_f32_e32 v68, v2, v62
	v_and_b32_e32 v62, 0xffff0000, v160
	v_fmac_f32_e32 v62, v2, v63
	v_cvt_pk_bf16_f32 v68, v68, v62
	v_add_f32_e32 v69, v71, v69
	v_and_b32_e32 v63, 0xffff0000, v68
	v_lshlrev_b32_e32 v62, 16, v68
	v_mul_f32_e32 v63, v63, v63
	v_fmac_f32_e32 v63, v62, v62
	v_add_f32_e32 v62, v69, v63
	v_lshlrev_b32_e32 v63, 16, v161
	v_fmac_f32_e32 v63, v2, v64
	v_and_b32_e32 v64, 0xffff0000, v161
	v_fmac_f32_e32 v64, v2, v65
	v_cvt_pk_bf16_f32 v69, v63, v64
	s_waitcnt vmcnt(14)
	v_lshlrev_b32_e32 v65, 16, v150
	v_and_b32_e32 v64, 0xffff0000, v69
	v_lshlrev_b32_e32 v63, 16, v69
	v_mul_f32_e32 v64, v64, v64
	v_fmac_f32_e32 v64, v63, v63
	v_add_f32_e32 v64, v62, v64
	v_lshl_add_u64 v[62:63], s[84:85], 0, v[220:221]
	v_fmac_f32_e32 v65, v2, v58
	v_and_b32_e32 v58, 0xffff0000, v150
	v_lshl_add_u64 v[62:63], v[62:63], 0, v[212:213]
	v_fmac_f32_e32 v58, v2, v59
	global_store_dwordx4 v[62:63], v[66:69], off
	v_cvt_pk_bf16_f32 v58, v65, v58
	s_nop 0
	v_and_b32_e32 v65, 0xffff0000, v58
	v_lshlrev_b32_e32 v59, 16, v58
	v_mul_f32_e32 v65, v65, v65
	v_fmac_f32_e32 v65, v59, v59
	v_lshlrev_b32_e32 v59, 16, v151
	v_fmac_f32_e32 v59, v2, v60
	v_and_b32_e32 v60, 0xffff0000, v151
	v_fmac_f32_e32 v60, v2, v61
	v_cvt_pk_bf16_f32 v59, v59, v60
	v_add_f32_e32 v64, v64, v65
	v_and_b32_e32 v61, 0xffff0000, v59
	v_lshlrev_b32_e32 v60, 16, v59
	v_mul_f32_e32 v61, v61, v61
	v_fmac_f32_e32 v61, v60, v60
	v_lshlrev_b32_e32 v60, 16, v152
	v_fmac_f32_e32 v60, v2, v54
	v_and_b32_e32 v54, 0xffff0000, v152
	v_fmac_f32_e32 v54, v2, v55
	v_cvt_pk_bf16_f32 v60, v60, v54
	v_add_f32_e32 v61, v64, v61
	v_and_b32_e32 v55, 0xffff0000, v60
	v_lshlrev_b32_e32 v54, 16, v60
	v_mul_f32_e32 v55, v55, v55
	v_fmac_f32_e32 v55, v54, v54
	v_add_f32_e32 v54, v61, v55
	v_lshlrev_b32_e32 v55, 16, v153
	v_fmac_f32_e32 v55, v2, v56
	v_and_b32_e32 v56, 0xffff0000, v153
	v_fmac_f32_e32 v56, v2, v57
	v_cvt_pk_bf16_f32 v61, v55, v56
	global_store_dwordx4 v[62:63], v[58:61], off offset:256
	v_and_b32_e32 v56, 0xffff0000, v61
	v_lshlrev_b32_e32 v55, 16, v61
	v_mul_f32_e32 v56, v56, v56
	v_fmac_f32_e32 v56, v55, v55
	s_waitcnt vmcnt(15)
	v_lshlrev_b32_e32 v55, 16, v146
	v_fmac_f32_e32 v55, v2, v50
	v_and_b32_e32 v50, 0xffff0000, v146
	v_fmac_f32_e32 v50, v2, v51
	v_cvt_pk_bf16_f32 v50, v55, v50
	v_add_f32_e32 v54, v54, v56
	v_and_b32_e32 v55, 0xffff0000, v50
	v_lshlrev_b32_e32 v51, 16, v50
	v_mul_f32_e32 v55, v55, v55
	v_fmac_f32_e32 v55, v51, v51
	v_lshlrev_b32_e32 v51, 16, v147
	v_fmac_f32_e32 v51, v2, v52
	v_and_b32_e32 v52, 0xffff0000, v147
	v_fmac_f32_e32 v52, v2, v53
	v_cvt_pk_bf16_f32 v51, v51, v52
	s_nop 0
	v_and_b32_e32 v53, 0xffff0000, v51
	v_lshlrev_b32_e32 v52, 16, v51
	v_mul_f32_e32 v53, v53, v53
	v_fmac_f32_e32 v53, v52, v52
	v_lshlrev_b32_e32 v52, 16, v148
	v_fmac_f32_e32 v52, v2, v46
	v_and_b32_e32 v46, 0xffff0000, v148
	v_fmac_f32_e32 v46, v2, v47
	v_cvt_pk_bf16_f32 v52, v52, v46
	v_add_f32_e32 v53, v55, v53
	v_and_b32_e32 v47, 0xffff0000, v52
	v_lshlrev_b32_e32 v46, 16, v52
	v_mul_f32_e32 v47, v47, v47
	v_fmac_f32_e32 v47, v46, v46
	v_add_f32_e32 v46, v53, v47
	v_lshlrev_b32_e32 v47, 16, v149
	v_fmac_f32_e32 v47, v2, v48
	v_and_b32_e32 v48, 0xffff0000, v149
	v_fmac_f32_e32 v48, v2, v49
	v_cvt_pk_bf16_f32 v53, v47, v48
	s_waitcnt vmcnt(14)
	v_lshlrev_b32_e32 v49, 16, v142
	v_and_b32_e32 v48, 0xffff0000, v53
	v_lshlrev_b32_e32 v47, 16, v53
	v_mul_f32_e32 v48, v48, v48
	v_fmac_f32_e32 v48, v47, v47
	v_add_f32_e32 v48, v46, v48
	v_lshl_add_u64 v[46:47], s[84:85], 0, v[218:219]
	v_fmac_f32_e32 v49, v2, v42
	v_and_b32_e32 v42, 0xffff0000, v142
	v_lshl_add_u64 v[46:47], v[46:47], 0, v[212:213]
	v_fmac_f32_e32 v42, v2, v43
	global_store_dwordx4 v[46:47], v[50:53], off
	v_cvt_pk_bf16_f32 v42, v49, v42
	s_nop 0
	v_and_b32_e32 v49, 0xffff0000, v42
	v_lshlrev_b32_e32 v43, 16, v42
	v_mul_f32_e32 v49, v49, v49
	v_fmac_f32_e32 v49, v43, v43
	v_lshlrev_b32_e32 v43, 16, v143
	v_fmac_f32_e32 v43, v2, v44
	v_and_b32_e32 v44, 0xffff0000, v143
	v_fmac_f32_e32 v44, v2, v45
	v_cvt_pk_bf16_f32 v43, v43, v44
	v_add_f32_e32 v48, v48, v49
	v_and_b32_e32 v45, 0xffff0000, v43
	v_lshlrev_b32_e32 v44, 16, v43
	v_mul_f32_e32 v45, v45, v45
	v_fmac_f32_e32 v45, v44, v44
	v_lshlrev_b32_e32 v44, 16, v144
	v_fmac_f32_e32 v44, v2, v38
	v_and_b32_e32 v38, 0xffff0000, v144
	v_fmac_f32_e32 v38, v2, v39
	v_cvt_pk_bf16_f32 v44, v44, v38
	v_add_f32_e32 v45, v48, v45
	v_and_b32_e32 v39, 0xffff0000, v44
	v_lshlrev_b32_e32 v38, 16, v44
	v_mul_f32_e32 v39, v39, v39
	v_fmac_f32_e32 v39, v38, v38
	v_add_f32_e32 v38, v45, v39
	v_lshlrev_b32_e32 v39, 16, v145
	v_fmac_f32_e32 v39, v2, v40
	v_and_b32_e32 v40, 0xffff0000, v145
	v_fmac_f32_e32 v40, v2, v41
	v_cvt_pk_bf16_f32 v45, v39, v40
	global_store_dwordx4 v[46:47], v[42:45], off offset:256
	v_and_b32_e32 v40, 0xffff0000, v45
	v_lshlrev_b32_e32 v39, 16, v45
	v_mul_f32_e32 v40, v40, v40
	v_fmac_f32_e32 v40, v39, v39
	s_waitcnt vmcnt(15)
; __device__ __forceinline__ unsigned cvt_pk_bf16(float lo, float hi) { unsigned r; asm volatile("v_cvt_pk_bf16_f32 %0, %1, %2" : "=v"(r) : "v"(lo), "v"(hi)); return r; }
;     __device__ __forceinline__ void operator()(const f32x4 (&acc)[2][2][4][2], const Unit& u, int wr, int wc, int fr, int fq) const {
;     ...
;             for (int m = 0; m < 4; ++m) {
;                 const int row = row0 + ai * HALF + m * 16;
;                 float ss = 0.f;
; #pragma unroll
;                 for (int bj = 0; bj < 2; ++bj) {
;                     const u32x4 xo = xv[ai][m][bj]; u32x4 w;
; #pragma unroll
;                     for (int k = 0; k < 4; ++k) {
;                         const float a0 = __uint_as_float(xo[k] << 16) + acc[ai][bj][m][k >> 1][(k & 1) * 2] * scale, a1 = __uint_as_float(xo[k] & 0xffff0000u) + acc[ai][bj][m][k >> 1][(k & 1) * 2 + 1] * scale;
;                         const unsigned p = cvt_pk_bf16(a0, a1); w[k] = p;
;                         const float r0 = __uint_as_float(p << 16), r1 = __uint_as_float(p & 0xffff0000u); ss += r0 * r0 + r1 * r1;
;                     }
;                     *(u32x4*)(xb + (size_t)row * 1024 + col0 + bj * HALF) = w;
;                 }
;                 ssv[ai][m] = ss;
;             }
; #pragma unroll
;         for (int ai = 0; ai < 2; ++ai)
; #pragma unroll
;             for (int m = 0; m < 4; ++m) ssv[ai][m] += __shfl_xor(ssv[ai][m], 16);
; #pragma unroll
;         for (int ai = 0; ai < 2; ++ai)
; #pragma unroll
;             for (int m = 0; m < 4; ++m) ssv[ai][m] += __shfl_xor(ssv[ai][m], 32);
	v_lshlrev_b32_e32 v39, 16, v138
	v_fmac_f32_e32 v39, v2, v34
	v_and_b32_e32 v34, 0xffff0000, v138
	v_fmac_f32_e32 v34, v2, v35
	v_cvt_pk_bf16_f32 v34, v39, v34
	v_add_f32_e32 v38, v38, v40
	v_and_b32_e32 v39, 0xffff0000, v34
	v_lshlrev_b32_e32 v35, 16, v34
	v_mul_f32_e32 v39, v39, v39
	v_fmac_f32_e32 v39, v35, v35
	v_lshlrev_b32_e32 v35, 16, v139
	v_fmac_f32_e32 v35, v2, v36
	v_and_b32_e32 v36, 0xffff0000, v139
	v_fmac_f32_e32 v36, v2, v37
	v_cvt_pk_bf16_f32 v35, v35, v36
	s_nop 0
	v_and_b32_e32 v37, 0xffff0000, v35
	v_lshlrev_b32_e32 v36, 16, v35
	v_mul_f32_e32 v37, v37, v37
	v_fmac_f32_e32 v37, v36, v36
	v_lshlrev_b32_e32 v36, 16, v140
	v_fmac_f32_e32 v36, v2, v30
	v_and_b32_e32 v30, 0xffff0000, v140
	v_fmac_f32_e32 v30, v2, v31
	v_cvt_pk_bf16_f32 v36, v36, v30
	v_add_f32_e32 v37, v39, v37
	v_and_b32_e32 v31, 0xffff0000, v36
	v_lshlrev_b32_e32 v30, 16, v36
	v_mul_f32_e32 v31, v31, v31
	v_fmac_f32_e32 v31, v30, v30
	v_add_f32_e32 v30, v37, v31
	v_lshlrev_b32_e32 v31, 16, v141
	v_fmac_f32_e32 v31, v2, v32
	v_and_b32_e32 v32, 0xffff0000, v141
	v_fmac_f32_e32 v32, v2, v33
	v_cvt_pk_bf16_f32 v37, v31, v32
	s_waitcnt vmcnt(14)
	v_lshlrev_b32_e32 v33, 16, v134
	v_and_b32_e32 v32, 0xffff0000, v37
	v_lshlrev_b32_e32 v31, 16, v37
	v_mul_f32_e32 v32, v32, v32
	v_fmac_f32_e32 v32, v31, v31
	v_add_f32_e32 v32, v30, v32
	v_lshl_add_u64 v[30:31], s[84:85], 0, v[216:217]
	v_fmac_f32_e32 v33, v2, v26
	v_and_b32_e32 v26, 0xffff0000, v134
	v_lshl_add_u64 v[30:31], v[30:31], 0, v[212:213]
	v_fmac_f32_e32 v26, v2, v27
	global_store_dwordx4 v[30:31], v[34:37], off
	v_cvt_pk_bf16_f32 v26, v33, v26
	s_nop 0
	v_and_b32_e32 v33, 0xffff0000, v26
	v_lshlrev_b32_e32 v27, 16, v26
	v_mul_f32_e32 v33, v33, v33
	v_fmac_f32_e32 v33, v27, v27
	v_lshlrev_b32_e32 v27, 16, v135
	v_fmac_f32_e32 v27, v2, v28
	v_and_b32_e32 v28, 0xffff0000, v135
	v_fmac_f32_e32 v28, v2, v29
	v_cvt_pk_bf16_f32 v27, v27, v28
	v_add_f32_e32 v32, v32, v33
	v_and_b32_e32 v29, 0xffff0000, v27
	v_lshlrev_b32_e32 v28, 16, v27
	v_mul_f32_e32 v29, v29, v29
	v_fmac_f32_e32 v29, v28, v28
	v_lshlrev_b32_e32 v28, 16, v136
	v_fmac_f32_e32 v28, v2, v22
	v_and_b32_e32 v22, 0xffff0000, v136
	v_fmac_f32_e32 v22, v2, v23
	v_cvt_pk_bf16_f32 v28, v28, v22
	v_add_f32_e32 v29, v32, v29
	v_and_b32_e32 v23, 0xffff0000, v28
	v_lshlrev_b32_e32 v22, 16, v28
	v_mul_f32_e32 v23, v23, v23
	v_fmac_f32_e32 v23, v22, v22
	v_add_f32_e32 v22, v29, v23
	v_lshlrev_b32_e32 v23, 16, v137
	v_fmac_f32_e32 v23, v2, v24
	v_and_b32_e32 v24, 0xffff0000, v137
	v_fmac_f32_e32 v24, v2, v25
	v_cvt_pk_bf16_f32 v29, v23, v24
	global_store_dwordx4 v[30:31], v[26:29], off offset:256
	v_and_b32_e32 v24, 0xffff0000, v29
	v_lshlrev_b32_e32 v23, 16, v29
	v_mul_f32_e32 v24, v24, v24
	v_fmac_f32_e32 v24, v23, v23
	s_waitcnt vmcnt(15)
	v_lshlrev_b32_e32 v23, 16, v130
	v_fmac_f32_e32 v23, v2, v18
	v_and_b32_e32 v18, 0xffff0000, v130
	v_fmac_f32_e32 v18, v2, v19
	v_cvt_pk_bf16_f32 v18, v23, v18
	v_add_f32_e32 v22, v22, v24
	v_and_b32_e32 v23, 0xffff0000, v18
	v_lshlrev_b32_e32 v19, 16, v18
	v_mul_f32_e32 v23, v23, v23
	v_fmac_f32_e32 v23, v19, v19
	v_lshlrev_b32_e32 v19, 16, v131
	v_fmac_f32_e32 v19, v2, v20
	v_and_b32_e32 v20, 0xffff0000, v131
	v_fmac_f32_e32 v20, v2, v21
	v_cvt_pk_bf16_f32 v19, v19, v20
	s_nop 0
	v_and_b32_e32 v21, 0xffff0000, v19
	v_lshlrev_b32_e32 v20, 16, v19
	v_mul_f32_e32 v21, v21, v21
	v_fmac_f32_e32 v21, v20, v20
	v_lshlrev_b32_e32 v20, 16, v132
	v_fmac_f32_e32 v20, v2, v14
	v_and_b32_e32 v14, 0xffff0000, v132
	v_fmac_f32_e32 v14, v2, v15
	v_cvt_pk_bf16_f32 v20, v20, v14
	v_add_f32_e32 v21, v23, v21
	v_and_b32_e32 v15, 0xffff0000, v20
	v_lshlrev_b32_e32 v14, 16, v20
	v_mul_f32_e32 v15, v15, v15
	v_fmac_f32_e32 v15, v14, v14
	v_add_f32_e32 v14, v21, v15
	v_lshlrev_b32_e32 v15, 16, v133
	v_fmac_f32_e32 v15, v2, v16
	v_and_b32_e32 v16, 0xffff0000, v133
	v_fmac_f32_e32 v16, v2, v17
	v_cvt_pk_bf16_f32 v21, v15, v16
	s_waitcnt vmcnt(14)
	v_lshlrev_b32_e32 v17, 16, v126
	v_and_b32_e32 v16, 0xffff0000, v21
	v_lshlrev_b32_e32 v15, 16, v21
	v_mul_f32_e32 v16, v16, v16
	v_fmac_f32_e32 v16, v15, v15
	v_add_f32_e32 v16, v14, v16
	v_lshl_add_u64 v[14:15], s[84:85], 0, v[214:215]
	v_fmac_f32_e32 v17, v2, v10
	v_and_b32_e32 v10, 0xffff0000, v126
	v_lshl_add_u64 v[14:15], v[14:15], 0, v[212:213]
	v_fmac_f32_e32 v10, v2, v11
	global_store_dwordx4 v[14:15], v[18:21], off
	v_cvt_pk_bf16_f32 v10, v17, v10
	s_nop 0
	v_and_b32_e32 v17, 0xffff0000, v10
	v_lshlrev_b32_e32 v11, 16, v10
	v_mul_f32_e32 v17, v17, v17
	v_fmac_f32_e32 v17, v11, v11
	v_lshlrev_b32_e32 v11, 16, v127
	v_fmac_f32_e32 v11, v2, v12
	v_and_b32_e32 v12, 0xffff0000, v127
	v_fmac_f32_e32 v12, v2, v13
	v_cvt_pk_bf16_f32 v11, v11, v12
	v_add_f32_e32 v16, v16, v17
	v_and_b32_e32 v13, 0xffff0000, v11
	v_lshlrev_b32_e32 v12, 16, v11
	v_mul_f32_e32 v13, v13, v13
	v_fmac_f32_e32 v13, v12, v12
	v_lshlrev_b32_e32 v12, 16, v128
	v_fmac_f32_e32 v12, v2, v6
	v_and_b32_e32 v6, 0xffff0000, v128
	v_fmac_f32_e32 v6, v2, v7
	v_cvt_pk_bf16_f32 v12, v12, v6
	v_add_f32_e32 v13, v16, v13
	v_and_b32_e32 v7, 0xffff0000, v12
	v_lshlrev_b32_e32 v6, 16, v12
	v_mul_f32_e32 v7, v7, v7
	v_fmac_f32_e32 v7, v6, v6
	v_add_f32_e32 v6, v13, v7
	v_lshlrev_b32_e32 v7, 16, v129
	v_fmac_f32_e32 v7, v2, v8
	v_and_b32_e32 v8, 0xffff0000, v129
	v_fmac_f32_e32 v8, v2, v9
	v_cvt_pk_bf16_f32 v13, v7, v8
	global_store_dwordx4 v[14:15], v[10:13], off offset:256
	v_and_b32_e32 v8, 0xffff0000, v13
	v_lshlrev_b32_e32 v7, 16, v13
	v_mul_f32_e32 v8, v8, v8
	v_fmac_f32_e32 v8, v7, v7
	v_and_b32_e32 v7, 64, v232
	v_add_f32_e32 v16, v6, v8
	v_xor_b32_e32 v6, 16, v232
	v_add_u32_e32 v13, 64, v7
	v_cmp_lt_i32_e32 vcc, v6, v13
	v_xor_b32_e32 v15, 32, v232
	s_nop 0
	v_cndmask_b32_e32 v6, v232, v6, vcc
	v_lshlrev_b32_e32 v14, 2, v6
	ds_bpermute_b32 v6, v14, v118
	ds_bpermute_b32 v7, v14, v102
	ds_bpermute_b32 v8, v14, v86
	ds_bpermute_b32 v9, v14, v70
	ds_bpermute_b32 v10, v14, v54
	ds_bpermute_b32 v11, v14, v38
	ds_bpermute_b32 v12, v14, v22
	ds_bpermute_b32 v14, v14, v16
	v_cmp_lt_i32_e32 vcc, v15, v13
	s_waitcnt lgkmcnt(7)
	v_add_f32_e32 v6, v118, v6
	s_waitcnt lgkmcnt(6)
	v_add_f32_e32 v7, v102, v7
	v_cndmask_b32_e32 v13, v232, v15, vcc
	s_waitcnt lgkmcnt(5)
	v_add_f32_e32 v8, v86, v8
	s_waitcnt lgkmcnt(4)
	v_add_f32_e32 v9, v70, v9
	s_waitcnt lgkmcnt(3)
	v_add_f32_e32 v10, v54, v10
	s_waitcnt lgkmcnt(2)
	v_add_f32_e32 v11, v38, v11
	s_waitcnt lgkmcnt(1)
	v_add_f32_e32 v12, v22, v12
	s_waitcnt lgkmcnt(0)
	v_add_f32_e32 v14, v16, v14
	v_lshlrev_b32_e32 v21, 2, v13
	ds_bpermute_b32 v13, v21, v6
	ds_bpermute_b32 v15, v21, v7
	ds_bpermute_b32 v16, v21, v8
	ds_bpermute_b32 v17, v21, v9
	ds_bpermute_b32 v18, v21, v10
	ds_bpermute_b32 v19, v21, v11
	ds_bpermute_b32 v20, v21, v12
	ds_bpermute_b32 v21, v21, v14
	s_and_saveexec_b64 s[10:11], s[38:39]
	s_movk_i32 s55, 0x1a00
	s_cbranch_execz .LBB0_182
;     __device__ __forceinline__ void operator()(const f32x4 (&acc)[2][2][4][2], const Unit& u, int wr, int wc, int fr, int fq) const {
;     ...
;         if (fq == 0 && fin) {
; #pragma unroll
;             for (int ai = 0; ai < 2; ++ai)
; #pragma unroll
;                 for (int m = 0; m < 4; ++m) unsafeAtomicAdd(rowss + row0 + ai * HALF + m * 16, ssv[ai][m]);
;         }
	s_waitcnt lgkmcnt(6)
	v_add_f32_e32 v15, v7, v15
	v_add_f32_e32 v13, v6, v13
	v_lshl_add_u64 v[6:7], v[210:211], 2, s[8:9]
	s_waitcnt lgkmcnt(0)
	v_add_f32_e32 v14, v14, v21
	v_add_f32_e32 v12, v12, v20
	v_add_f32_e32 v11, v11, v19
	v_add_f32_e32 v10, v10, v18
	v_add_f32_e32 v9, v9, v17
	v_add_f32_e32 v8, v8, v16
	global_atomic_add_f32 v[6:7], v13, off
	global_atomic_add_f32 v[6:7], v15, off offset:64
	global_atomic_add_f32 v[6:7], v8, off offset:128
	global_atomic_add_f32 v[6:7], v9, off offset:192
	global_atomic_add_f32 v[6:7], v10, off offset:512
	global_atomic_add_f32 v[6:7], v11, off offset:576
	global_atomic_add_f32 v[6:7], v12, off offset:640
	global_atomic_add_f32 v[6:7], v14, off offset:704
